# MLP down-projection GEMM epilogue (gate*(acc+bias)) also regrouped through LDS; all four main GEMM epilogues now store 4 rows x 256 B per instruction
# speedup vs baseline: 1.0173x; 1.0094x over previous
; __device__ __forceinline__ unsigned pk2(float lo, float hi) { const v2f_t f = {lo, hi}; const v2bf_t b = __builtin_convertvector(f, v2bf_t); return __builtin_bit_cast(unsigned, b); }
;     __device__ __forceinline__ void operator()(const f32x4 (&acc)[2][2][4][2], const Unit& u, int wr, int wc, int fr, int fq) const {
;     ...
;         const int mr = u.pm < 64 ? (u.pm >> 4) : 4;
;         const float* gp = gate + (size_t)mr * 6 * D + col0;
;         f32x4 gv[2][2], bv[2][2];
; #pragma unroll
;         for (int bj = 0; bj < 2; ++bj)
; #pragma unroll
;             for (int n = 0; n < 2; ++n) { gv[bj][n] = *(const f32x4*)(gp + bj * 128 + 4 * n); bv[bj][n] = bias ? *(const f32x4*)(bias + col0 + bj * 128 + 4 * n) : (f32x4){0.f, 0.f, 0.f, 0.f}; }
; #pragma unroll
;         for (int ai = 0; ai < 2; ++ai)
; #pragma unroll
;             for (int m = 0; m < 4; ++m) { bf16_t* rowp = delta + (size_t)(row0 + ai * 128 + m * 16) * D + col0;
; #pragma unroll
;                 for (int bj = 0; bj < 2; ++bj) { const f32x4 v0 = gv[bj][0] * (acc[ai][bj][m][0] + bv[bj][0]), v1 = gv[bj][1] * (acc[ai][bj][m][1] + bv[bj][1]);
;                     u32x4 w; w.x = pk2(v0[0], v0[1]); w.y = pk2(v0[2], v0[3]); w.z = pk2(v1[0], v1[1]); w.w = pk2(v1[2], v1[3]);
;                     *(u32x4*)(rowp + bj * 128) = w; } }
.LBB0_973:
	v_and_b32_e32 v183, 15, v194
	v_bfe_u32 v184, v194, 6, 2
	v_bfe_u32 v185, v194, 4, 2
	v_bfe_u32 v218, v194, 8, 1
	v_lshlrev_b32_e32 v218, 4, v218
	v_add_u32_e32 v218, v218, v183
	v_mul_u32_u24_e32 v212, 0x110, v218
	v_lshl_add_u32 v212, v184, 6, v212
	v_lshl_add_u32 v212, v185, 4, v212
	v_add_u32_e32 v212, 0x23410, v212
	v_lshrrev_b32_e32 v218, 6, v194
	v_lshl_add_u32 v218, v218, 2, v185
	v_mul_u32_u24_e32 v213, 0x110, v218
	v_lshl_add_u32 v213, v183, 4, v213
	v_add_u32_e32 v213, 0x23410, v213
	v_sub_u32_e32 v218, v182, v183
	v_lshl_add_u32 v218, v184, 2, v218
	v_add_u32_e32 v218, v218, v185
	v_lshlrev_b32_e32 v218, 12, v218
	v_and_b32_e32 v219, 0xffffff00, v180
	v_lshlrev_b32_e32 v219, 1, v219
	v_lshl_add_u32 v219, v183, 4, v219
	v_add_u32_e32 v218, v218, v219
	v_mov_b32_e32 v219, 0
	v_lshl_add_u64 v[214:215], s[2:3], 0, v[218:219]
	s_mov_b32 s11, 0
	s_mov_b64 s[20:21], 0
	s_waitcnt vmcnt(0)
	s_mov_b32 s10, 0x0
	v_lshl_add_u64 v[216:217], v[214:215], 0, s[10:11]
	v_pk_add_f32 v[126:127], v[126:127], v[138:139]
	v_pk_add_f32 v[128:129], v[128:129], v[140:141]
	v_pk_mul_f32 v[126:127], v[134:135], v[126:127]
	v_pk_mul_f32 v[128:129], v[136:137], v[128:129]
	v_pk_add_f32 v[122:123], v[122:123], v[130:131]
	v_pk_add_f32 v[124:125], v[124:125], v[132:133]
	v_pk_mul_f32 v[122:123], v[142:143], v[122:123]
	v_pk_mul_f32 v[124:125], v[144:145], v[124:125]
	v_cvt_pk_bf16_f32 v190, v126, v127
	v_cvt_pk_bf16_f32 v191, v128, v129
	v_cvt_pk_bf16_f32 v192, v122, v123
	v_cvt_pk_bf16_f32 v193, v124, v125
	ds_write_b128 v212, v[190:193]
	s_waitcnt lgkmcnt(0)
	s_barrier
	ds_read_b128 v[204:207], v213
	s_waitcnt lgkmcnt(0)
	global_store_dwordx4 v[216:217], v[204:207], off
	v_pk_add_f32 v[118:119], v[118:119], v[154:155]
	v_pk_add_f32 v[120:121], v[120:121], v[156:157]
	v_pk_mul_f32 v[118:119], v[150:151], v[118:119]
	v_pk_mul_f32 v[120:121], v[152:153], v[120:121]
	v_pk_add_f32 v[114:115], v[114:115], v[146:147]
	v_pk_add_f32 v[116:117], v[116:117], v[148:149]
	v_pk_mul_f32 v[114:115], v[158:159], v[114:115]
	v_pk_mul_f32 v[116:117], v[160:161], v[116:117]
	v_cvt_pk_bf16_f32 v190, v118, v119
	v_cvt_pk_bf16_f32 v191, v120, v121
	v_cvt_pk_bf16_f32 v192, v114, v115
	v_cvt_pk_bf16_f32 v193, v116, v117
	ds_write_b128 v212, v[190:193] offset:8704
	s_waitcnt lgkmcnt(0)
	s_barrier
	ds_read_b128 v[208:211], v213 offset:8704
	s_waitcnt lgkmcnt(0)
	global_store_dwordx4 v[216:217], v[208:211], off offset:256
	s_mov_b32 s10, 0x10000
	v_lshl_add_u64 v[216:217], v[214:215], 0, s[10:11]
	v_pk_add_f32 v[110:111], v[110:111], v[138:139]
	v_pk_add_f32 v[112:113], v[112:113], v[140:141]
	v_pk_mul_f32 v[110:111], v[134:135], v[110:111]
	v_pk_mul_f32 v[112:113], v[136:137], v[112:113]
	v_pk_add_f32 v[106:107], v[106:107], v[130:131]
	v_pk_add_f32 v[108:109], v[108:109], v[132:133]
	v_pk_mul_f32 v[106:107], v[142:143], v[106:107]
	v_pk_mul_f32 v[108:109], v[144:145], v[108:109]
	v_cvt_pk_bf16_f32 v190, v110, v111
	v_cvt_pk_bf16_f32 v191, v112, v113
	v_cvt_pk_bf16_f32 v192, v106, v107
	v_cvt_pk_bf16_f32 v193, v108, v109
	ds_write_b128 v212, v[190:193]
	s_waitcnt lgkmcnt(0)
	s_barrier
	ds_read_b128 v[204:207], v213
	s_waitcnt lgkmcnt(0)
	global_store_dwordx4 v[216:217], v[204:207], off
	v_pk_add_f32 v[102:103], v[102:103], v[154:155]
	v_pk_add_f32 v[104:105], v[104:105], v[156:157]
	v_pk_mul_f32 v[102:103], v[150:151], v[102:103]
	v_pk_mul_f32 v[104:105], v[152:153], v[104:105]
	v_pk_add_f32 v[98:99], v[98:99], v[146:147]
	v_pk_add_f32 v[100:101], v[100:101], v[148:149]
	v_pk_mul_f32 v[98:99], v[158:159], v[98:99]
	v_pk_mul_f32 v[100:101], v[160:161], v[100:101]
	v_cvt_pk_bf16_f32 v190, v102, v103
	v_cvt_pk_bf16_f32 v191, v104, v105
	v_cvt_pk_bf16_f32 v192, v98, v99
	v_cvt_pk_bf16_f32 v193, v100, v101
	ds_write_b128 v212, v[190:193] offset:8704
	s_waitcnt lgkmcnt(0)
	s_barrier
	ds_read_b128 v[208:211], v213 offset:8704
	s_waitcnt lgkmcnt(0)
	global_store_dwordx4 v[216:217], v[208:211], off offset:256
	s_mov_b32 s10, 0x20000
	v_lshl_add_u64 v[216:217], v[214:215], 0, s[10:11]
	v_pk_add_f32 v[94:95], v[94:95], v[138:139]
	v_pk_add_f32 v[96:97], v[96:97], v[140:141]
	v_pk_mul_f32 v[94:95], v[134:135], v[94:95]
	v_pk_mul_f32 v[96:97], v[136:137], v[96:97]
	v_pk_add_f32 v[90:91], v[90:91], v[130:131]
	v_pk_add_f32 v[92:93], v[92:93], v[132:133]
	v_pk_mul_f32 v[90:91], v[142:143], v[90:91]
	v_pk_mul_f32 v[92:93], v[144:145], v[92:93]
	v_cvt_pk_bf16_f32 v190, v94, v95
	v_cvt_pk_bf16_f32 v191, v96, v97
	v_cvt_pk_bf16_f32 v192, v90, v91
	v_cvt_pk_bf16_f32 v193, v92, v93
	ds_write_b128 v212, v[190:193]
	s_waitcnt lgkmcnt(0)
	s_barrier
	ds_read_b128 v[204:207], v213
	s_waitcnt lgkmcnt(0)
	global_store_dwordx4 v[216:217], v[204:207], off
	v_pk_add_f32 v[86:87], v[86:87], v[154:155]
	v_pk_add_f32 v[88:89], v[88:89], v[156:157]
	v_pk_mul_f32 v[86:87], v[150:151], v[86:87]
	v_pk_mul_f32 v[88:89], v[152:153], v[88:89]
	v_pk_add_f32 v[82:83], v[82:83], v[146:147]
	v_pk_add_f32 v[84:85], v[84:85], v[148:149]
	v_pk_mul_f32 v[82:83], v[158:159], v[82:83]
	v_pk_mul_f32 v[84:85], v[160:161], v[84:85]
	v_cvt_pk_bf16_f32 v190, v86, v87
	v_cvt_pk_bf16_f32 v191, v88, v89
	v_cvt_pk_bf16_f32 v192, v82, v83
	v_cvt_pk_bf16_f32 v193, v84, v85
	ds_write_b128 v212, v[190:193] offset:8704
	s_waitcnt lgkmcnt(0)
	s_barrier
	ds_read_b128 v[208:211], v213 offset:8704
	s_waitcnt lgkmcnt(0)
	global_store_dwordx4 v[216:217], v[208:211], off offset:256
	s_mov_b32 s10, 0x30000
	v_lshl_add_u64 v[216:217], v[214:215], 0, s[10:11]
	v_pk_add_f32 v[78:79], v[78:79], v[138:139]
	v_pk_add_f32 v[80:81], v[80:81], v[140:141]
	v_pk_mul_f32 v[78:79], v[134:135], v[78:79]
	v_pk_mul_f32 v[80:81], v[136:137], v[80:81]
	v_pk_add_f32 v[74:75], v[74:75], v[130:131]
	v_pk_add_f32 v[76:77], v[76:77], v[132:133]
	v_pk_mul_f32 v[74:75], v[142:143], v[74:75]
	v_pk_mul_f32 v[76:77], v[144:145], v[76:77]
	v_cvt_pk_bf16_f32 v190, v78, v79
	v_cvt_pk_bf16_f32 v191, v80, v81
	v_cvt_pk_bf16_f32 v192, v74, v75
	v_cvt_pk_bf16_f32 v193, v76, v77
	ds_write_b128 v212, v[190:193]
	s_waitcnt lgkmcnt(0)
	s_barrier
; __device__ __forceinline__ unsigned pk2(float lo, float hi) { const v2f_t f = {lo, hi}; const v2bf_t b = __builtin_convertvector(f, v2bf_t); return __builtin_bit_cast(unsigned, b); }
;     __device__ __forceinline__ void operator()(const f32x4 (&acc)[2][2][4][2], const Unit& u, int wr, int wc, int fr, int fq) const {
;     ...
;         for (int ai = 0; ai < 2; ++ai)
; #pragma unroll
;             for (int m = 0; m < 4; ++m) { bf16_t* rowp = delta + (size_t)(row0 + ai * 128 + m * 16) * D + col0;
; #pragma unroll
;                 for (int bj = 0; bj < 2; ++bj) { const f32x4 v0 = gv[bj][0] * (acc[ai][bj][m][0] + bv[bj][0]), v1 = gv[bj][1] * (acc[ai][bj][m][1] + bv[bj][1]);
;                     u32x4 w; w.x = pk2(v0[0], v0[1]); w.y = pk2(v0[2], v0[3]); w.z = pk2(v1[0], v1[1]); w.w = pk2(v1[2], v1[3]);
;                     *(u32x4*)(rowp + bj * 128) = w; } }
	ds_read_b128 v[204:207], v213
	s_waitcnt lgkmcnt(0)
	global_store_dwordx4 v[216:217], v[204:207], off
	v_pk_add_f32 v[70:71], v[70:71], v[154:155]
	v_pk_add_f32 v[72:73], v[72:73], v[156:157]
	v_pk_mul_f32 v[70:71], v[150:151], v[70:71]
	v_pk_mul_f32 v[72:73], v[152:153], v[72:73]
	v_pk_add_f32 v[66:67], v[66:67], v[146:147]
	v_pk_add_f32 v[68:69], v[68:69], v[148:149]
	v_pk_mul_f32 v[66:67], v[158:159], v[66:67]
	v_pk_mul_f32 v[68:69], v[160:161], v[68:69]
	v_cvt_pk_bf16_f32 v190, v70, v71
	v_cvt_pk_bf16_f32 v191, v72, v73
	v_cvt_pk_bf16_f32 v192, v66, v67
	v_cvt_pk_bf16_f32 v193, v68, v69
	ds_write_b128 v212, v[190:193] offset:8704
	s_waitcnt lgkmcnt(0)
	s_barrier
	ds_read_b128 v[208:211], v213 offset:8704
	s_waitcnt lgkmcnt(0)
	global_store_dwordx4 v[216:217], v[208:211], off offset:256
	s_mov_b32 s10, 0x80000
	v_lshl_add_u64 v[216:217], v[214:215], 0, s[10:11]
	v_pk_add_f32 v[60:61], v[60:61], v[138:139]
	v_pk_add_f32 v[62:63], v[62:63], v[140:141]
	v_pk_mul_f32 v[60:61], v[134:135], v[60:61]
	v_pk_mul_f32 v[62:63], v[136:137], v[62:63]
	v_pk_add_f32 v[56:57], v[56:57], v[130:131]
	v_pk_add_f32 v[58:59], v[58:59], v[132:133]
	v_pk_mul_f32 v[56:57], v[142:143], v[56:57]
	v_pk_mul_f32 v[58:59], v[144:145], v[58:59]
	v_cvt_pk_bf16_f32 v190, v60, v61
	v_cvt_pk_bf16_f32 v191, v62, v63
	v_cvt_pk_bf16_f32 v192, v56, v57
	v_cvt_pk_bf16_f32 v193, v58, v59
	ds_write_b128 v212, v[190:193]
	s_waitcnt lgkmcnt(0)
	s_barrier
	ds_read_b128 v[204:207], v213
	s_waitcnt lgkmcnt(0)
	global_store_dwordx4 v[216:217], v[204:207], off
	v_pk_add_f32 v[52:53], v[52:53], v[154:155]
	v_pk_add_f32 v[54:55], v[54:55], v[156:157]
	v_pk_mul_f32 v[52:53], v[150:151], v[52:53]
	v_pk_mul_f32 v[54:55], v[152:153], v[54:55]
	v_pk_add_f32 v[48:49], v[48:49], v[146:147]
	v_pk_add_f32 v[50:51], v[50:51], v[148:149]
	v_pk_mul_f32 v[48:49], v[158:159], v[48:49]
	v_pk_mul_f32 v[50:51], v[160:161], v[50:51]
	v_cvt_pk_bf16_f32 v190, v52, v53
	v_cvt_pk_bf16_f32 v191, v54, v55
	v_cvt_pk_bf16_f32 v192, v48, v49
	v_cvt_pk_bf16_f32 v193, v50, v51
	ds_write_b128 v212, v[190:193] offset:8704
	s_waitcnt lgkmcnt(0)
	s_barrier
	ds_read_b128 v[208:211], v213 offset:8704
	s_waitcnt lgkmcnt(0)
	global_store_dwordx4 v[216:217], v[208:211], off offset:256
	s_mov_b32 s10, 0x90000
	v_lshl_add_u64 v[216:217], v[214:215], 0, s[10:11]
	v_pk_add_f32 v[44:45], v[44:45], v[138:139]
	v_pk_add_f32 v[46:47], v[46:47], v[140:141]
	v_pk_mul_f32 v[44:45], v[134:135], v[44:45]
	v_pk_mul_f32 v[46:47], v[136:137], v[46:47]
	v_pk_add_f32 v[40:41], v[40:41], v[130:131]
	v_pk_add_f32 v[42:43], v[42:43], v[132:133]
	v_pk_mul_f32 v[40:41], v[142:143], v[40:41]
	v_pk_mul_f32 v[42:43], v[144:145], v[42:43]
	v_cvt_pk_bf16_f32 v190, v44, v45
	v_cvt_pk_bf16_f32 v191, v46, v47
	v_cvt_pk_bf16_f32 v192, v40, v41
	v_cvt_pk_bf16_f32 v193, v42, v43
	ds_write_b128 v212, v[190:193]
	s_waitcnt lgkmcnt(0)
	s_barrier
	ds_read_b128 v[204:207], v213
	s_waitcnt lgkmcnt(0)
	global_store_dwordx4 v[216:217], v[204:207], off
	v_pk_add_f32 v[36:37], v[36:37], v[154:155]
	v_pk_add_f32 v[38:39], v[38:39], v[156:157]
	v_pk_mul_f32 v[36:37], v[150:151], v[36:37]
	v_pk_mul_f32 v[38:39], v[152:153], v[38:39]
	v_pk_add_f32 v[32:33], v[32:33], v[146:147]
	v_pk_add_f32 v[34:35], v[34:35], v[148:149]
	v_pk_mul_f32 v[32:33], v[158:159], v[32:33]
	v_pk_mul_f32 v[34:35], v[160:161], v[34:35]
	v_cvt_pk_bf16_f32 v190, v36, v37
	v_cvt_pk_bf16_f32 v191, v38, v39
	v_cvt_pk_bf16_f32 v192, v32, v33
	v_cvt_pk_bf16_f32 v193, v34, v35
	ds_write_b128 v212, v[190:193] offset:8704
	s_waitcnt lgkmcnt(0)
	s_barrier
	ds_read_b128 v[208:211], v213 offset:8704
	s_waitcnt lgkmcnt(0)
	global_store_dwordx4 v[216:217], v[208:211], off offset:256
	s_mov_b32 s10, 0xa0000
	v_lshl_add_u64 v[216:217], v[214:215], 0, s[10:11]
	v_pk_add_f32 v[28:29], v[28:29], v[138:139]
	v_pk_add_f32 v[30:31], v[30:31], v[140:141]
	v_pk_mul_f32 v[28:29], v[134:135], v[28:29]
	v_pk_mul_f32 v[30:31], v[136:137], v[30:31]
	v_pk_add_f32 v[24:25], v[24:25], v[130:131]
	v_pk_add_f32 v[26:27], v[26:27], v[132:133]
	v_pk_mul_f32 v[24:25], v[142:143], v[24:25]
	v_pk_mul_f32 v[26:27], v[144:145], v[26:27]
	v_cvt_pk_bf16_f32 v190, v28, v29
	v_cvt_pk_bf16_f32 v191, v30, v31
	v_cvt_pk_bf16_f32 v192, v24, v25
	v_cvt_pk_bf16_f32 v193, v26, v27
	ds_write_b128 v212, v[190:193]
	s_waitcnt lgkmcnt(0)
	s_barrier
	ds_read_b128 v[204:207], v213
	s_waitcnt lgkmcnt(0)
	global_store_dwordx4 v[216:217], v[204:207], off
	v_pk_add_f32 v[20:21], v[20:21], v[154:155]
	v_pk_add_f32 v[22:23], v[22:23], v[156:157]
	v_pk_mul_f32 v[20:21], v[150:151], v[20:21]
	v_pk_mul_f32 v[22:23], v[152:153], v[22:23]
	v_pk_add_f32 v[16:17], v[16:17], v[146:147]
	v_pk_add_f32 v[18:19], v[18:19], v[148:149]
	v_pk_mul_f32 v[16:17], v[158:159], v[16:17]
	v_pk_mul_f32 v[18:19], v[160:161], v[18:19]
	v_cvt_pk_bf16_f32 v190, v20, v21
	v_cvt_pk_bf16_f32 v191, v22, v23
	v_cvt_pk_bf16_f32 v192, v16, v17
	v_cvt_pk_bf16_f32 v193, v18, v19
	ds_write_b128 v212, v[190:193] offset:8704
	s_waitcnt lgkmcnt(0)
	s_barrier
	ds_read_b128 v[208:211], v213 offset:8704
	s_waitcnt lgkmcnt(0)
	global_store_dwordx4 v[216:217], v[208:211], off offset:256
	s_mov_b32 s10, 0xb0000
	v_lshl_add_u64 v[216:217], v[214:215], 0, s[10:11]
	v_pk_add_f32 v[12:13], v[12:13], v[138:139]
	v_pk_add_f32 v[14:15], v[14:15], v[140:141]
	v_pk_mul_f32 v[12:13], v[134:135], v[12:13]
	v_pk_mul_f32 v[14:15], v[136:137], v[14:15]
	v_pk_add_f32 v[8:9], v[8:9], v[130:131]
	v_pk_add_f32 v[10:11], v[10:11], v[132:133]
	v_pk_mul_f32 v[8:9], v[142:143], v[8:9]
	v_pk_mul_f32 v[10:11], v[144:145], v[10:11]
	v_cvt_pk_bf16_f32 v190, v12, v13
	v_cvt_pk_bf16_f32 v191, v14, v15
	v_cvt_pk_bf16_f32 v192, v8, v9
	v_cvt_pk_bf16_f32 v193, v10, v11
	ds_write_b128 v212, v[190:193]
	s_waitcnt lgkmcnt(0)
	s_barrier
	ds_read_b128 v[204:207], v213
	s_waitcnt lgkmcnt(0)
	global_store_dwordx4 v[216:217], v[204:207], off
	v_pk_add_f32 v[4:5], v[4:5], v[154:155]
	v_pk_add_f32 v[6:7], v[6:7], v[156:157]
	v_pk_mul_f32 v[4:5], v[150:151], v[4:5]
	v_pk_mul_f32 v[6:7], v[152:153], v[6:7]
	v_pk_add_f32 v[0:1], v[0:1], v[146:147]
	v_pk_add_f32 v[2:3], v[2:3], v[148:149]
	v_pk_mul_f32 v[0:1], v[158:159], v[0:1]
	v_pk_mul_f32 v[2:3], v[160:161], v[2:3]
	v_cvt_pk_bf16_f32 v190, v4, v5
	v_cvt_pk_bf16_f32 v191, v6, v7
	v_cvt_pk_bf16_f32 v192, v0, v1
	v_cvt_pk_bf16_f32 v193, v2, v3
	ds_write_b128 v212, v[190:193] offset:8704
	s_waitcnt lgkmcnt(0)
	s_barrier
	ds_read_b128 v[208:211], v213 offset:8704
	s_waitcnt lgkmcnt(0)
	global_store_dwordx4 v[216:217], v[208:211], off offset:256
